# softmax scale-subtract as packed fma at all sites (row max moved into the low half of a temp pair), zero-initialised row-sum adds merged
# speedup vs baseline: 1.0032x; 1.0032x over previous
.LBB0_590:
	v_mov_b64_e32 v[154:155], v[2:3]
	v_mov_b32_e32 v2, v3
	v_pk_fma_f32 v[136:137], v[136:137], s[98:99], v[152:153] op_sel_hi:[1,1,0] neg_lo:[0,0,1] neg_hi:[0,0,1]
	v_pk_fma_f32 v[138:139], v[138:139], s[98:99], v[152:153] op_sel_hi:[1,1,0] neg_lo:[0,0,1] neg_hi:[0,0,1]
	v_pk_fma_f32 v[132:133], v[132:133], s[98:99], v[152:153] op_sel_hi:[1,1,0] neg_lo:[0,0,1] neg_hi:[0,0,1]
	v_pk_fma_f32 v[134:135], v[134:135], s[98:99], v[152:153] op_sel_hi:[1,1,0] neg_lo:[0,0,1] neg_hi:[0,0,1]
	v_exp_f32_e32 v136, v136
	v_exp_f32_e32 v137, v137
	v_exp_f32_e32 v138, v138
	v_exp_f32_e32 v139, v139
	v_exp_f32_e32 v168, v132
	v_exp_f32_e32 v169, v133
	v_exp_f32_e32 v170, v134
	v_exp_f32_e32 v171, v135
	v_cvt_pk_bf16_f32 v134, v168, v169
	v_pk_add_f32 v[166:167], v[138:139], v[136:137]
	v_pk_fma_f32 v[124:125], v[124:125], s[98:99], v[2:3] op_sel_hi:[1,1,0] neg_lo:[0,0,1] neg_hi:[0,0,1]
	v_pk_add_f32 v[132:133], v[168:169], v[166:167]
	v_pk_fma_f32 v[126:127], v[126:127], s[98:99], v[2:3] op_sel_hi:[1,1,0] neg_lo:[0,0,1] neg_hi:[0,0,1]
	v_pk_add_f32 v[132:133], v[170:171], v[132:133]
	v_pk_fma_f32 v[128:129], v[128:129], s[98:99], v[2:3] op_sel_hi:[1,1,0] neg_lo:[0,0,1] neg_hi:[0,0,1]
	v_pk_fma_f32 v[130:131], v[130:131], s[98:99], v[2:3] op_sel_hi:[1,1,0] neg_lo:[0,0,1] neg_hi:[0,0,1]
	v_add_f32_e32 v2, v132, v133
	v_add_f32_e32 v0, v0, v2
	v_add_u32_e32 v2, s28, v160
	v_add_u32_e32 v152, v2, v159
	ds_read_b128 v[166:169], v152 offset:8192
	v_exp_f32_e32 v124, v124
	v_exp_f32_e32 v125, v125
	v_exp_f32_e32 v126, v126
	v_exp_f32_e32 v127, v127
	v_exp_f32_e32 v128, v128
	v_exp_f32_e32 v129, v129
	v_exp_f32_e32 v130, v130
	v_exp_f32_e32 v131, v131
	v_cvt_pk_bf16_f32 v132, v136, v137
	v_cvt_pk_bf16_f32 v133, v138, v139
	v_cvt_pk_bf16_f32 v135, v170, v171
	ds_read_b128 v[170:173], v152 offset:10240
	v_cvt_pk_bf16_f32 v136, v124, v125
	v_cvt_pk_bf16_f32 v137, v126, v127
	v_cvt_pk_bf16_f32 v138, v128, v129
	v_cvt_pk_bf16_f32 v139, v130, v131
	v_pk_add_f32 v[124:125], v[126:127], v[124:125]
	s_nop 0
	v_pk_add_f32 v[124:125], v[128:129], v[124:125]
	s_nop 0
	v_pk_add_f32 v[124:125], v[130:131], v[124:125]
	s_nop 0
	v_add_f32_e32 v124, v124, v125
	ds_read_b128 v[126:129], v152 offset:12288
	s_waitcnt lgkmcnt(2)
	v_mfma_f32_16x16x32_bf16 v[80:83], v[166:169], v[132:135], v[80:83]
	v_mfma_f32_16x16x32_bf16 v[76:79], v[166:169], v[136:139], v[76:79]
	ds_read_b128 v[166:169], v152 offset:14336
	s_waitcnt lgkmcnt(2)
	v_mfma_f32_16x16x32_bf16 v[72:75], v[170:173], v[132:135], v[72:75]
	v_mfma_f32_16x16x32_bf16 v[68:71], v[170:173], v[136:139], v[68:71]
	ds_read_b128 v[170:173], v152 offset:16384
	s_waitcnt lgkmcnt(2)
	v_mfma_f32_16x16x32_bf16 v[64:67], v[126:129], v[132:135], v[64:67]
	v_mfma_f32_16x16x32_bf16 v[60:63], v[126:129], v[136:139], v[60:63]
	ds_read_b128 v[126:129], v152 offset:18432
	s_waitcnt lgkmcnt(2)
	v_mfma_f32_16x16x32_bf16 v[56:59], v[166:169], v[132:135], v[56:59]
	v_mfma_f32_16x16x32_bf16 v[52:55], v[166:169], v[136:139], v[52:55]
	ds_read_b128 v[166:169], v152 offset:20480
	s_waitcnt lgkmcnt(2)
	v_mfma_f32_16x16x32_bf16 v[48:51], v[170:173], v[132:135], v[48:51]
	v_mfma_f32_16x16x32_bf16 v[44:47], v[170:173], v[136:139], v[44:47]
	ds_read_b128 v[170:173], v152 offset:22528
	s_waitcnt lgkmcnt(2)
	v_mfma_f32_16x16x32_bf16 v[40:43], v[126:129], v[132:135], v[40:43]
	v_mfma_f32_16x16x32_bf16 v[32:35], v[126:129], v[136:139], v[32:35]
	s_waitcnt lgkmcnt(1)
	v_mfma_f32_16x16x32_bf16 v[36:39], v[166:169], v[132:135], v[36:39]
	v_mfma_f32_16x16x32_bf16 v[24:27], v[166:169], v[136:139], v[24:27]
	s_waitcnt lgkmcnt(0)
	v_mfma_f32_16x16x32_bf16 v[28:31], v[170:173], v[132:135], v[28:31]
	v_max3_f32 v132, v116, v117, v118
	v_add_f32_e32 v133, 0x41000000, v165
	v_max3_f32 v132, v132, v119, v120
	v_mfma_f32_16x16x32_bf16 v[20:23], v[170:173], v[136:139], v[20:23]
	v_max3_f32 v132, v132, v121, v122
	s_nop 0
	v_max3_f32 v132, v132, v123, v123
	s_nop 0
	v_mul_f32_e32 v132, 0x3e38aa3b, v132
	v_cmp_gt_f32_e32 vcc, v132, v133
	s_cbranch_vccz .LBB0_592
	ds_swizzle_b32 v3, v132 offset:swizzle(SWAP,16)
	v_max_f32_e32 v132, v132, v132
	s_waitcnt lgkmcnt(0)
	v_max_f32_e32 v3, v3, v3
	v_max_f32_e32 v3, v132, v3
	ds_bpermute_b32 v132, v156, v3
	s_waitcnt lgkmcnt(0)
	v_max3_f32 v154, v165, v3, v132
	v_sub_f32_e32 v3, v165, v154
	v_exp_f32_e32 v132, v3
	v_mov_b32_e32 v3, v155
	v_mov_b32_e32 v165, v154
	v_mul_f32_e32 v0, v0, v132
	v_pk_mul_f32 v[82:83], v[82:83], v[132:133] op_sel_hi:[1,0]
	v_pk_mul_f32 v[80:81], v[80:81], v[132:133] op_sel_hi:[1,0]
	v_pk_mul_f32 v[74:75], v[74:75], v[132:133] op_sel_hi:[1,0]
	v_pk_mul_f32 v[72:73], v[72:73], v[132:133] op_sel_hi:[1,0]
	v_pk_mul_f32 v[66:67], v[66:67], v[132:133] op_sel_hi:[1,0]
	v_pk_mul_f32 v[64:65], v[64:65], v[132:133] op_sel_hi:[1,0]
	v_pk_mul_f32 v[58:59], v[58:59], v[132:133] op_sel_hi:[1,0]
	v_pk_mul_f32 v[56:57], v[56:57], v[132:133] op_sel_hi:[1,0]
	v_pk_mul_f32 v[50:51], v[50:51], v[132:133] op_sel_hi:[1,0]
	v_pk_mul_f32 v[48:49], v[48:49], v[132:133] op_sel_hi:[1,0]
	v_pk_mul_f32 v[42:43], v[42:43], v[132:133] op_sel_hi:[1,0]
	v_pk_mul_f32 v[40:41], v[40:41], v[132:133] op_sel_hi:[1,0]
	v_pk_mul_f32 v[38:39], v[38:39], v[132:133] op_sel_hi:[1,0]
	v_pk_mul_f32 v[36:37], v[36:37], v[132:133] op_sel_hi:[1,0]
	v_pk_mul_f32 v[30:31], v[30:31], v[132:133] op_sel_hi:[1,0]
	v_pk_mul_f32 v[28:29], v[28:29], v[132:133] op_sel_hi:[1,0]

.LBB0_594:
	v_mov_b32_e32 v130, v165
	v_mov_b32_e32 v128, v3
	v_pk_fma_f32 v[116:117], v[116:117], s[98:99], v[130:131] op_sel_hi:[1,1,0] neg_lo:[0,0,1] neg_hi:[0,0,1]
	v_pk_fma_f32 v[118:119], v[118:119], s[98:99], v[130:131] op_sel_hi:[1,1,0] neg_lo:[0,0,1] neg_hi:[0,0,1]
	v_pk_fma_f32 v[120:121], v[120:121], s[98:99], v[130:131] op_sel_hi:[1,1,0] neg_lo:[0,0,1] neg_hi:[0,0,1]
	v_pk_fma_f32 v[108:109], v[108:109], s[98:99], v[128:129] op_sel_hi:[1,1,0] neg_lo:[0,0,1] neg_hi:[0,0,1]
	v_exp_f32_e32 v116, v116
	v_exp_f32_e32 v117, v117
	v_exp_f32_e32 v118, v118
	v_exp_f32_e32 v119, v119
	v_pk_fma_f32 v[110:111], v[110:111], s[98:99], v[128:129] op_sel_hi:[1,1,0] neg_lo:[0,0,1] neg_hi:[0,0,1]
	v_exp_f32_e32 v120, v120
	v_exp_f32_e32 v121, v121
	v_exp_f32_e32 v108, v108
	v_exp_f32_e32 v109, v109
	v_pk_fma_f32 v[112:113], v[112:113], s[98:99], v[128:129] op_sel_hi:[1,1,0] neg_lo:[0,0,1] neg_hi:[0,0,1]
	v_exp_f32_e32 v110, v110
	v_exp_f32_e32 v111, v111
	v_exp_f32_e32 v112, v112
	v_exp_f32_e32 v113, v113
	v_pk_fma_f32 v[114:115], v[114:115], s[98:99], v[128:129] op_sel_hi:[1,1,0] neg_lo:[0,0,1] neg_hi:[0,0,1]
	v_pk_add_f32 v[126:127], v[118:119], v[116:117]
	v_exp_f32_e32 v114, v114
	v_exp_f32_e32 v115, v115
	v_pk_add_f32 v[126:127], v[120:121], v[126:127]
	v_cvt_pk_bf16_f32 v116, v116, v117
	v_cvt_pk_bf16_f32 v117, v118, v119
	v_cvt_pk_bf16_f32 v118, v120, v121
	v_add_u32_e32 v2, v2, v157
	v_pk_add_f32 v[120:121], v[110:111], v[108:109]
	v_cvt_pk_bf16_f32 v108, v108, v109
	v_pk_add_f32 v[120:121], v[112:113], v[120:121]
	v_cvt_pk_bf16_f32 v109, v110, v111
	v_pk_add_f32 v[120:121], v[114:115], v[120:121]
	v_cvt_pk_bf16_f32 v110, v112, v113
	v_cvt_pk_bf16_f32 v111, v114, v115
	ds_read_b128 v[112:115], v2 offset:8192
	ds_read_b128 v[128:131], v2 offset:10240
	ds_read_b128 v[132:135], v2 offset:12288
	ds_read_b128 v[136:139], v2 offset:14336
	v_fma_f32 v122, v122, s72, -v165
	v_fma_f32 v123, v123, s72, -v165
	s_nop 0
	v_exp_f32_e32 v122, v122
	v_exp_f32_e32 v123, v123
	s_waitcnt lgkmcnt(3)
	v_mfma_f32_16x16x32_bf16 v[76:79], v[112:115], v[108:111], v[76:79]
	v_cvt_pk_bf16_f32 v119, v122, v123
	s_bitcmp1_b32 s21, 0
	s_cselect_b32 s0, 0x6000, 0
	v_mfma_f32_16x16x32_bf16 v[80:83], v[112:115], v[116:119], v[80:83]
	ds_read_b128 v[112:115], v2 offset:16384
	v_pk_add_f32 v[126:127], v[122:123], v[126:127]
	s_add_i32 s0, s0, 0
	s_waitcnt lgkmcnt(3)
	v_mfma_f32_16x16x32_bf16 v[72:75], v[128:131], v[116:119], v[72:75]
	v_add_f32_e32 v125, v126, v127
	v_add_f32_e32 v120, v120, v121
	v_mov_b64_e32 v[152:153], v[154:155]
	v_mfma_f32_16x16x32_bf16 v[68:71], v[128:131], v[108:111], v[68:71]
	ds_read_b128 v[128:131], v2 offset:18432
	v_add_f32_e32 v0, v0, v125
	v_add_f32_e32 v158, v124, v120
	s_waitcnt lgkmcnt(3)
	v_mfma_f32_16x16x32_bf16 v[64:67], v[132:135], v[116:119], v[64:67]
	s_cmpk_eq_i32 s19, 0x10c0
	v_mfma_f32_16x16x32_bf16 v[60:63], v[132:135], v[108:111], v[60:63]
	ds_read_b128 v[132:135], v2 offset:20480
	s_waitcnt lgkmcnt(3)
	v_mfma_f32_16x16x32_bf16 v[56:59], v[136:139], v[116:119], v[56:59]
	v_mfma_f32_16x16x32_bf16 v[52:55], v[136:139], v[108:111], v[52:55]
	ds_read_b128 v[136:139], v2 offset:22528
	s_waitcnt lgkmcnt(3)
	v_mfma_f32_16x16x32_bf16 v[48:51], v[112:115], v[116:119], v[48:51]
	v_mfma_f32_16x16x32_bf16 v[44:47], v[112:115], v[108:111], v[44:47]
	s_waitcnt lgkmcnt(2)
	v_mfma_f32_16x16x32_bf16 v[40:43], v[128:131], v[116:119], v[40:43]
	v_mfma_f32_16x16x32_bf16 v[32:35], v[128:131], v[108:111], v[32:35]
	v_add_u32_e32 v2, s0, v164
	s_waitcnt vmcnt(5)
	ds_write_b128 v2, v[84:87]
	s_waitcnt vmcnt(4)
	ds_write_b128 v2, v[88:91] offset:4096
	s_waitcnt lgkmcnt(3)
	v_mfma_f32_16x16x32_bf16 v[36:39], v[132:135], v[116:119], v[36:39]
	v_mfma_f32_16x16x32_bf16 v[24:27], v[132:135], v[108:111], v[24:27]
	v_add3_u32 v2, s0, v163, v162
	s_waitcnt vmcnt(3)
	ds_write_b128 v2, v[92:95] offset:8192
	s_waitcnt vmcnt(1)
	ds_write_b128 v2, v[96:99] offset:12288
	s_waitcnt lgkmcnt(4)
	v_mfma_f32_16x16x32_bf16 v[28:31], v[136:139], v[116:119], v[28:31]
	s_waitcnt vmcnt(0)
	ds_write_b128 v2, v[100:103] offset:16384
	ds_write_b128 v2, v[104:107] offset:20480
	v_mfma_f32_16x16x32_bf16 v[20:23], v[136:139], v[108:111], v[20:23]
	s_cbranch_scc1 .LBB0_596
	s_mov_b32 s0, s21
	s_branch .LBB0_580

.LBB0_617:
	v_mov_b64_e32 v[2:3], v[194:195]
	v_mov_b32_e32 v226, v195
	v_pk_fma_f32 v[170:171], v[170:171], s[98:99], v[196:197] op_sel_hi:[1,1,0] neg_lo:[0,0,1] neg_hi:[0,0,1]
	v_pk_fma_f32 v[172:173], v[172:173], s[98:99], v[196:197] op_sel_hi:[1,1,0] neg_lo:[0,0,1] neg_hi:[0,0,1]
	v_pk_fma_f32 v[166:167], v[166:167], s[98:99], v[196:197] op_sel_hi:[1,1,0] neg_lo:[0,0,1] neg_hi:[0,0,1]
	v_pk_fma_f32 v[168:169], v[168:169], s[98:99], v[196:197] op_sel_hi:[1,1,0] neg_lo:[0,0,1] neg_hi:[0,0,1]
	v_exp_f32_e32 v170, v170
	v_exp_f32_e32 v171, v171
	v_exp_f32_e32 v172, v172
	v_exp_f32_e32 v173, v173
	v_exp_f32_e32 v166, v166
	v_exp_f32_e32 v167, v167
	v_exp_f32_e32 v214, v168
	v_exp_f32_e32 v215, v169
	v_pk_add_f32 v[212:213], v[172:173], v[170:171]
	v_pk_fma_f32 v[158:159], v[158:159], s[98:99], v[226:227] op_sel_hi:[1,1,0] neg_lo:[0,0,1] neg_hi:[0,0,1]
	v_pk_add_f32 v[168:169], v[166:167], v[212:213]
	v_pk_fma_f32 v[160:161], v[160:161], s[98:99], v[226:227] op_sel_hi:[1,1,0] neg_lo:[0,0,1] neg_hi:[0,0,1]
	v_pk_add_f32 v[168:169], v[214:215], v[168:169]
	v_pk_fma_f32 v[162:163], v[162:163], s[98:99], v[226:227] op_sel_hi:[1,1,0] neg_lo:[0,0,1] neg_hi:[0,0,1]
	v_pk_fma_f32 v[164:165], v[164:165], s[98:99], v[226:227] op_sel_hi:[1,1,0] neg_lo:[0,0,1] neg_hi:[0,0,1]
	v_add_f32_e32 v168, v168, v169
	v_add_f32_e32 v0, v0, v168
	v_cvt_pk_bf16_f32 v168, v170, v171
	v_cvt_pk_bf16_f32 v170, v166, v167
	v_add_u32_e32 v166, s24, v206
	v_add_u32_e32 v167, v166, v205
	ds_read_b128 v[234:237], v167 offset:8192
	v_exp_f32_e32 v158, v158
	v_exp_f32_e32 v159, v159
	v_exp_f32_e32 v160, v160
	v_exp_f32_e32 v161, v161
	v_exp_f32_e32 v162, v162
	v_exp_f32_e32 v163, v163
	v_exp_f32_e32 v164, v164
	v_exp_f32_e32 v165, v165
	v_cvt_pk_bf16_f32 v169, v172, v173
	v_cvt_pk_bf16_f32 v171, v214, v215
	ds_read_b128 v[212:215], v167 offset:10240
	v_cvt_pk_bf16_f32 v226, v158, v159
	v_cvt_pk_bf16_f32 v227, v160, v161
	v_cvt_pk_bf16_f32 v228, v162, v163
	v_cvt_pk_bf16_f32 v229, v164, v165
	v_pk_add_f32 v[158:159], v[160:161], v[158:159]
	s_nop 0
	v_pk_add_f32 v[158:159], v[162:163], v[158:159]
	s_nop 0
	v_pk_add_f32 v[158:159], v[164:165], v[158:159]
	s_nop 0
	v_add_f32_e32 v158, v158, v159
	ds_read_b128 v[160:163], v167 offset:12288
	s_waitcnt lgkmcnt(2)
	v_mfma_f32_16x16x32_bf16 v[114:117], v[234:237], v[168:171], v[114:117]
	v_mfma_f32_16x16x32_bf16 v[110:113], v[234:237], v[226:229], v[110:113]
	ds_read_b128 v[234:237], v167 offset:14336
	s_waitcnt lgkmcnt(2)
	v_mfma_f32_16x16x32_bf16 v[106:109], v[212:215], v[168:171], v[106:109]
	v_mfma_f32_16x16x32_bf16 v[102:105], v[212:215], v[226:229], v[102:105]
	ds_read_b128 v[212:215], v167 offset:16384
	s_waitcnt lgkmcnt(2)
	v_mfma_f32_16x16x32_bf16 v[98:101], v[160:163], v[168:171], v[98:101]
	v_mfma_f32_16x16x32_bf16 v[94:97], v[160:163], v[226:229], v[94:97]
	ds_read_b128 v[160:163], v167 offset:18432
	s_waitcnt lgkmcnt(2)
	v_mfma_f32_16x16x32_bf16 v[90:93], v[234:237], v[168:171], v[90:93]
	v_mfma_f32_16x16x32_bf16 v[86:89], v[234:237], v[226:229], v[86:89]
	ds_read_b128 v[234:237], v167 offset:20480
	s_waitcnt lgkmcnt(2)
	v_mfma_f32_16x16x32_bf16 v[82:85], v[212:215], v[168:171], v[82:85]
	v_mfma_f32_16x16x32_bf16 v[78:81], v[212:215], v[226:229], v[78:81]
	ds_read_b128 v[212:215], v167 offset:22528
	s_waitcnt lgkmcnt(2)
	v_mfma_f32_16x16x32_bf16 v[74:77], v[160:163], v[168:171], v[74:77]
	v_mfma_f32_16x16x32_bf16 v[66:69], v[160:163], v[226:229], v[66:69]
	s_waitcnt lgkmcnt(1)
	v_mfma_f32_16x16x32_bf16 v[70:73], v[234:237], v[168:171], v[70:73]
	v_mfma_f32_16x16x32_bf16 v[58:61], v[234:237], v[226:229], v[58:61]
	v_max3_f32 v167, v150, v151, v152
	s_nop 0
	v_max3_f32 v167, v167, v153, v154
	s_waitcnt lgkmcnt(0)
	v_mfma_f32_16x16x32_bf16 v[62:65], v[212:215], v[168:171], v[62:65]
	v_max3_f32 v167, v167, v155, v156
	v_add_f32_e32 v168, 0x41000000, v179
	v_max3_f32 v167, v167, v157, v157
	v_mfma_f32_16x16x32_bf16 v[54:57], v[212:215], v[226:229], v[54:57]
	v_mul_f32_e32 v167, 0x3e38aa3b, v167
	v_cmp_gt_f32_e32 vcc, v167, v168
	s_cbranch_vccz .LBB0_619
	ds_swizzle_b32 v2, v167 offset:swizzle(SWAP,16)
	v_max_f32_e32 v167, v167, v167
	v_mov_b32_e32 v195, v3
	s_waitcnt lgkmcnt(0)
	v_max_f32_e32 v2, v2, v2
	v_max_f32_e32 v2, v167, v2
	ds_bpermute_b32 v167, v202, v2
	s_waitcnt lgkmcnt(0)
	v_max3_f32 v2, v179, v2, v167
	v_sub_f32_e32 v167, v179, v2
	v_exp_f32_e32 v168, v167
	v_mov_b32_e32 v179, v2
	v_mul_f32_e32 v0, v0, v168
	v_pk_mul_f32 v[116:117], v[116:117], v[168:169] op_sel_hi:[1,0]
	v_pk_mul_f32 v[114:115], v[114:115], v[168:169] op_sel_hi:[1,0]
	v_pk_mul_f32 v[108:109], v[108:109], v[168:169] op_sel_hi:[1,0]
	v_pk_mul_f32 v[106:107], v[106:107], v[168:169] op_sel_hi:[1,0]
	v_pk_mul_f32 v[100:101], v[100:101], v[168:169] op_sel_hi:[1,0]
	v_pk_mul_f32 v[98:99], v[98:99], v[168:169] op_sel_hi:[1,0]
	v_pk_mul_f32 v[92:93], v[92:93], v[168:169] op_sel_hi:[1,0]
	v_pk_mul_f32 v[90:91], v[90:91], v[168:169] op_sel_hi:[1,0]
	v_pk_mul_f32 v[84:85], v[84:85], v[168:169] op_sel_hi:[1,0]
	v_pk_mul_f32 v[82:83], v[82:83], v[168:169] op_sel_hi:[1,0]
	v_pk_mul_f32 v[76:77], v[76:77], v[168:169] op_sel_hi:[1,0]
	v_pk_mul_f32 v[74:75], v[74:75], v[168:169] op_sel_hi:[1,0]
	v_pk_mul_f32 v[72:73], v[72:73], v[168:169] op_sel_hi:[1,0]
	v_pk_mul_f32 v[70:71], v[70:71], v[168:169] op_sel_hi:[1,0]
	v_pk_mul_f32 v[64:65], v[64:65], v[168:169] op_sel_hi:[1,0]
	v_pk_mul_f32 v[62:63], v[62:63], v[168:169] op_sel_hi:[1,0]

.LBB0_621:
	v_mov_b64_e32 v[196:197], v[2:3]
	v_mov_b32_e32 v2, v179
	v_mov_b32_e32 v212, v195
	v_pk_fma_f32 v[150:151], v[150:151], s[98:99], v[2:3] op_sel_hi:[1,1,0] neg_lo:[0,0,1] neg_hi:[0,0,1]
	v_pk_fma_f32 v[152:153], v[152:153], s[98:99], v[2:3] op_sel_hi:[1,1,0] neg_lo:[0,0,1] neg_hi:[0,0,1]
	v_pk_fma_f32 v[154:155], v[154:155], s[98:99], v[2:3] op_sel_hi:[1,1,0] neg_lo:[0,0,1] neg_hi:[0,0,1]
	v_pk_fma_f32 v[156:157], v[156:157], s[98:99], v[2:3] op_sel_hi:[1,1,0] neg_lo:[0,0,1] neg_hi:[0,0,1]
	v_exp_f32_e32 v2, v150
	v_exp_f32_e32 v3, v151
	v_exp_f32_e32 v152, v152
	v_exp_f32_e32 v153, v153
	v_exp_f32_e32 v154, v154
	v_exp_f32_e32 v155, v155
	v_exp_f32_e32 v156, v156
	v_exp_f32_e32 v157, v157
	v_pk_fma_f32 v[146:147], v[146:147], s[98:99], v[212:213] op_sel_hi:[1,1,0] neg_lo:[0,0,1] neg_hi:[0,0,1]
	v_pk_add_f32 v[150:151], v[152:153], v[2:3]
	v_pk_fma_f32 v[142:143], v[142:143], s[98:99], v[212:213] op_sel_hi:[1,1,0] neg_lo:[0,0,1] neg_hi:[0,0,1]
	v_pk_add_f32 v[150:151], v[154:155], v[150:151]
	v_exp_f32_e32 v146, v146
	v_pk_add_f32 v[150:151], v[156:157], v[150:151]
	v_exp_f32_e32 v147, v147
	v_add_f32_e32 v150, v150, v151
	v_add_f32_e32 v0, v0, v150
	v_cvt_pk_bf16_f32 v150, v2, v3
	v_pk_fma_f32 v[144:145], v[144:145], s[98:99], v[212:213] op_sel_hi:[1,1,0] neg_lo:[0,0,1] neg_hi:[0,0,1]
	v_pk_fma_f32 v[148:149], v[148:149], s[98:99], v[212:213] op_sel_hi:[1,1,0] neg_lo:[0,0,1] neg_hi:[0,0,1]
	v_exp_f32_e32 v2, v142
	v_exp_f32_e32 v3, v143
	v_exp_f32_e32 v144, v144
	v_exp_f32_e32 v145, v145
	v_exp_f32_e32 v148, v148
	v_exp_f32_e32 v149, v149
	v_cvt_pk_bf16_f32 v151, v152, v153
	v_pk_add_f32 v[142:143], v[144:145], v[2:3]
	v_cvt_pk_bf16_f32 v152, v154, v155
	v_pk_add_f32 v[142:143], v[146:147], v[142:143]
	v_cvt_pk_bf16_f32 v153, v156, v157
	v_pk_add_f32 v[142:143], v[148:149], v[142:143]
	s_bitcmp1_b32 s21, 0
	v_add_f32_e32 v142, v142, v143
	v_add_f32_e32 v204, v158, v142
	v_cvt_pk_bf16_f32 v142, v2, v3
	v_add_u32_e32 v2, v166, v203
	v_cvt_pk_bf16_f32 v143, v144, v145
	v_cvt_pk_bf16_f32 v144, v146, v147
	v_cvt_pk_bf16_f32 v145, v148, v149
	ds_read_b128 v[146:149], v2 offset:8192
	ds_read_b128 v[234:237], v2 offset:10240
	ds_read_b128 v[226:229], v2 offset:12288
	ds_read_b128 v[212:215], v2 offset:14336
	s_waitcnt lgkmcnt(3)
	v_mfma_f32_16x16x32_bf16 v[114:117], v[146:149], v[150:153], v[114:117]
	s_cselect_b32 s0, 0x6000, 0
	s_add_i32 s0, s0, 0
	s_cmpk_eq_i32 s19, 0x10c0
	v_mfma_f32_16x16x32_bf16 v[110:113], v[146:149], v[142:145], v[110:113]
	ds_read_b128 v[146:149], v2 offset:16384
	s_waitcnt lgkmcnt(3)
	v_mfma_f32_16x16x32_bf16 v[106:109], v[234:237], v[150:153], v[106:109]
	v_mfma_f32_16x16x32_bf16 v[102:105], v[234:237], v[142:145], v[102:105]
	ds_read_b128 v[234:237], v2 offset:18432
	s_waitcnt lgkmcnt(3)
	v_mfma_f32_16x16x32_bf16 v[98:101], v[226:229], v[150:153], v[98:101]
	v_mfma_f32_16x16x32_bf16 v[94:97], v[226:229], v[142:145], v[94:97]
	ds_read_b128 v[226:229], v2 offset:20480
	s_waitcnt lgkmcnt(3)
	v_mfma_f32_16x16x32_bf16 v[90:93], v[212:215], v[150:153], v[90:93]
	v_mfma_f32_16x16x32_bf16 v[86:89], v[212:215], v[142:145], v[86:89]
	ds_read_b128 v[212:215], v2 offset:22528
	s_waitcnt lgkmcnt(3)
	v_mfma_f32_16x16x32_bf16 v[82:85], v[146:149], v[150:153], v[82:85]
	v_mfma_f32_16x16x32_bf16 v[78:81], v[146:149], v[142:145], v[78:81]
	s_waitcnt lgkmcnt(2)
	v_mfma_f32_16x16x32_bf16 v[74:77], v[234:237], v[150:153], v[74:77]
	v_mfma_f32_16x16x32_bf16 v[66:69], v[234:237], v[142:145], v[66:69]
	v_add_u32_e32 v2, s0, v210
	s_waitcnt vmcnt(5)
	ds_write_b128 v2, v[118:121]
	s_waitcnt vmcnt(4)
	ds_write_b128 v2, v[122:125] offset:4096
	s_waitcnt lgkmcnt(3)
	v_mfma_f32_16x16x32_bf16 v[70:73], v[226:229], v[150:153], v[70:73]
	v_mfma_f32_16x16x32_bf16 v[58:61], v[226:229], v[142:145], v[58:61]
	v_add3_u32 v2, s0, v208, v209
	s_waitcnt vmcnt(3)
	ds_write_b128 v2, v[126:129] offset:8192
	s_waitcnt vmcnt(1)
	ds_write_b128 v2, v[130:133] offset:12288
	s_waitcnt lgkmcnt(4)
	v_mfma_f32_16x16x32_bf16 v[62:65], v[212:215], v[150:153], v[62:65]
	s_waitcnt vmcnt(0)
	ds_write_b128 v2, v[134:137] offset:16384
	ds_write_b128 v2, v[138:141] offset:20480
	v_mfma_f32_16x16x32_bf16 v[54:57], v[212:215], v[142:145], v[54:57]
	s_cbranch_scc1 .LBB0_623
	s_mov_b32 s0, s21
	s_branch .LBB0_607
